# graded phase-8 priorities: pre-step 0, u-side 1, v-side 2
# speedup vs baseline: 1.0093x; 1.0093x over previous
; __device__ void phase_gather_u(const Params& p) {
;   const int tid = threadIdx.x, lane = tid & 63, wid = tid >> 6;
;   unsigned char* ws = p.ws;
;   const unsigned char* ub = ws + OFF_XB;
;   const int* idxg = (const int*)(ws + OFF_IDX);
;   u32x4* xq = (u32x4*)(ws + OFF_XQ);
;   int* wbuf = (int*)(ws + OFF_WBUF);
;   float* sxa = (float*)(ws + OFF_WBUF + 8 * MIB);
;   const bool b5 = (lane & 32) != 0, b4 = (lane & 16) != 0, b3 = (lane & 8) != 0;
;   const int srcl = ((lane & 1) << 3) | (((lane >> 1) & 1) << 4) | (((lane >> 2) & 1) << 5);
;   const int tbase = blockIdx.x * 8 + wid, tstride = gridDim.x * 8;
;     ...
;   asm volatile("s_waitcnt vmcnt(0)" ::: "memory");
; #pragma unroll 1
;   for (int r = 0; r < 4; ++r) {
; #pragma unroll 1
;     for (int t = tbase; t < T_TOK; t += tstride) {
;       const u32x4 ph = xq[((size_t)t * 64 + lane) * 2], pl = xq[((size_t)t * 64 + lane) * 2 + 1];
;       const int idA = idxg[(size_t)t * 128 + lane], idB = idxg[(size_t)t * 128 + 64 + lane];
;       unsigned long long m0 = __ballot((idA >> 12) == r), m1 = __ballot((idB >> 12) == r);
.LBB0_1205:
	s_or_b64 exec, exec, s[4:5]
	v_and_b32_e32 v0, 32, v139
	v_cmp_eq_u32_e64 s[2:3], 0, v0
	v_and_b32_e32 v0, 16, v139
	v_cmp_eq_u32_e64 s[4:5], 0, v0
	v_and_b32_e32 v0, 8, v139
	s_add_u32 s10, s34, 0xc000000
	v_cmp_eq_u32_e64 s[6:7], 0, v0
	v_mov_b32_e32 v1, 0
	v_lshlrev_b32_e32 v0, 5, v138
	s_addc_u32 s11, s35, 0
	s_waitcnt lgkmcnt(0)
	v_lshl_add_u64 v[2:3], s[34:35], 0, v[0:1]
	v_lshlrev_b32_e32 v0, 2, v138
	v_lshlrev_b32_e32 v82, 3, v139
	v_writelane_b32 v250, s10, 18
	v_mbcnt_hi_u32_b32 v83, -1, v30
	v_and_b32_e32 v4, 56, v82
	v_lshl_add_u64 v[76:77], s[10:11], 0, v[0:1]
	v_lshlrev_b32_e32 v0, 4, v138
	s_waitcnt vmcnt(0)
	v_lshl_add_u64 v[72:73], s[34:35], 0, v[0:1]
	v_and_b32_e32 v0, 64, v83
	s_add_u32 s70, s34, 0x17400000
	s_mov_b64 s[8:9], 0x15400000
	v_add_u32_e32 v84, 64, v0
	v_or_b32_e32 v0, v0, v4
	s_addc_u32 s71, s35, 0
	s_mov_b32 s33, 0
	v_lshl_add_u64 v[74:75], v[2:3], 0, s[8:9]
	v_writelane_b32 v250, s11, 19
	v_cmp_gt_u32_e64 s[8:9], 8, v138
	v_cmp_eq_u32_e64 s[10:11], 1, v138
	v_cmp_eq_u32_e64 s[12:13], 2, v138
	v_cmp_eq_u32_e64 s[14:15], 3, v138
	v_cmp_eq_u32_e64 s[16:17], 4, v138
	v_cmp_eq_u32_e64 s[18:19], 5, v138
	v_cmp_eq_u32_e64 s[20:21], 6, v138
	v_cmp_eq_u32_e64 s[22:23], 7, v138
	s_movk_i32 s48, 0x3fff
	v_xor_b32_e32 v89, 32, v83
	v_xor_b32_e32 v90, 16, v83
	v_xor_b32_e32 v88, 8, v83
	v_xor_b32_e32 v87, 4, v83
	v_xor_b32_e32 v86, 2, v83
	v_xor_b32_e32 v85, 1, v83
	v_lshlrev_b32_e32 v91, 2, v0
	v_and_b32_e32 v96, 15, v138
	v_lshrrev_b32_e32 v99, 4, v138
	v_lshlrev_b32_e32 v98, 2, v138
	v_lshrrev_b32_e32 v100, 6, v139
	v_cmp_eq_u32_e64 s[8:9], 0, v96
	v_lshlrev_b32_e32 v97, 5, v96
	v_lshlrev_b32_e32 v96, 4, v96
	v_readfirstlane_b32 s60, v100
	v_readfirstlane_b32 s61, v112
	s_add_u32 s64, s34, 0x15400000
	s_addc_u32 s65, s35, 0
	s_add_u32 s62, s34, 0xc000000
	s_addc_u32 s63, s35, 0
	s_lshl_b32 s60, s60, 10
	s_and_saveexec_b64 s[38:39], s[0:1]
	s_cbranch_execz .Lgu_done
	s_mov_b32 s33, 0
	s_mov_b32 s66, 0
	s_lshl_b32 s72, s60, 4
	s_add_i32 s72, s72, 0x2000
	s_lshl_b32 s40, s61, 9
	s_add_u32 s40, s62, s40
	s_addc_u32 s41, s63, 0
	global_load_dword v94, v98, s[40:41]
	global_load_dword v95, v98, s[40:41] offset:256
	s_add_i32 s37, s61, s68
	s_lshl_b32 s40, s37, 9
	s_add_u32 s40, s62, s40
	s_addc_u32 s41, s63, 0
	global_load_dword v232, v98, s[40:41]
	global_load_dword v233, v98, s[40:41] offset:256
	s_waitcnt vmcnt(2)
	s_mov_b32 s67, 0xfffffc00
	s_setprio 1
